# P9: blocks owning a split-K sample tile run it first (stagger residual epilogues); plus P10/P4b latency fixes
# speedup vs baseline: 1.0080x; 1.0057x over previous
.LBB0_2085:
	s_or_b64 exec, exec, s[4:5]
	s_andn2_b64 vcc, exec, s[16:17]
	v_readlane_b32 s4, v254, 54
	s_waitcnt lgkmcnt(0)
	s_barrier
	v_readlane_b32 s5, v254, 55
	s_cbranch_vccnz .LBB0_2125
	s_add_u32 s2, s50, 0x38c0000
	s_addc_u32 s7, s51, 0
	v_readlane_b32 s8, v254, 50
	s_mov_b32 s34, s4
	s_add_u32 s4, s50, 0x47f0000
	v_readlane_b32 s9, v254, 51
	s_addc_u32 s5, s51, 0
	s_add_i32 s6, s8, 0xffffff00
	s_lshl_b32 s33, s8, 6
	s_lshl_b32 s56, s34, 6
	s_mov_b32 s9, 0
	s_movk_i32 s57, 0x2000
	s_movk_i32 s78, 0x6000
	s_mov_b64 s[10:11], 0x80
	s_mov_b64 s[12:13], 0x2d3cd780
	s_mov_b64 s[16:17], 0x38c0100
	s_mov_b64 s[18:19], 0x2d34d800
	s_mov_b64 s[20:21], 0x3940100
	s_mov_b64 s[22:23], 0x2d3cd800
	s_mov_b64 s[24:25], 0x38c0180
	s_mov_b64 s[26:27], 0x2d34d880
	s_mov_b64 s[28:29], 0x3940180
	s_mov_b64 s[30:31], 0x100
	v_mov_b32_e32 v129, 0
	s_mov_b64 s[38:39], 0x200000
	s_mov_b32 s79, 0x200000
	s_mov_b64 s[40:41], 0x240000
	s_mov_b32 s80, 0x240000
	s_mov_b64 s[42:43], 0x280000
	s_mov_b32 s81, 0x280000
	s_mov_b64 s[44:45], 0x2c0000
	s_mov_b64 s[52:53], 0x2b3cd780
	s_mov_b64 s[54:55], 0x2b34d800
	s_mov_b64 s[58:59], 0x2b3cd800
	s_mov_b64 s[60:61], 0x2b34d880
	v_mov_b32_e32 v148, 1
	s_mov_b32 s82, s8
	s_mov_b32 s84, s8
	s_mov_b32 s98, s34
	s_mov_b32 s99, s8
	s_cmpk_lt_u32 s8, 0x40
	s_cbranch_scc0 .Lp9_noswap
	s_movk_i32 s98, 0xff00
	s_add_i32 s99, s8, 0x100
	s_mov_b32 s82, s99
	s_mov_b32 s84, s99
	s_mov_b32 s6, s8
	s_lshl_b32 s33, s99, 6
.Lp9_noswap:
	s_lshl_b32 s100, s98, 6
	s_branch .LBB0_2089

.LBB0_2088:
	v_readlane_b32 s64, v254, 54
	s_mov_b32 s34, s64
	s_add_i32 s82, s82, s98
	s_add_i32 s6, s6, s98
	s_add_i32 s33, s33, s100
	s_and_b64 vcc, exec, s[62:63]
	s_mov_b32 s84, s83
	v_readlane_b32 s65, v254, 55
	s_cbranch_vccnz .LBB0_2125
.LBB0_2089:
	s_add_i32 s83, s84, s98
	s_cmpk_gt_u32 s83, 0x13f
	s_cselect_b64 s[62:63], -1, 0
	s_and_b64 vcc, exec, s[62:63]
	s_mov_b64 s[66:67], 0
	s_mov_b64 s[64:65], 0
	s_cbranch_vccnz .LBB0_2098
	s_cmpk_gt_i32 s83, 0xff
	s_mov_b64 s[68:69], -1
	s_cbranch_scc0 .LBB0_2092
	s_add_i32 s8, s83, 0xffffff00
	s_lshl_b32 s64, s83, 18
	s_lshr_b32 s8, s8, 3
	s_and_b32 s64, s64, 0x100000
	s_add_u32 s64, s50, s64
	s_addc_u32 s65, s51, 0
	s_lshl_b32 s66, s83, 10
	s_and_b32 s68, s66, 0xc00
	s_add_u32 s64, s64, s68
	s_addc_u32 s65, s65, 0
	s_add_u32 s64, s64, 0x2d34d700
	s_addc_u32 s65, s65, 0
	s_lshl_b64 s[66:67], s[8:9], 20
	s_add_u32 s8, s2, s66
	s_addc_u32 s67, s7, s67
	s_add_u32 s66, s8, s68
	s_addc_u32 s67, s67, 0
	s_mov_b64 s[68:69], 0

.LBB0_2098:
	s_cmpk_gt_i32 s84, 0xff
	s_mov_b64 s[68:69], -1
	s_cbranch_scc0 .LBB0_2110
	v_mov_b32_e32 v8, v250
	s_add_i32 s8, s84, 0xffffff00
	v_bfe_i32 v1, v8, 27, 1
	v_lshlrev_b32_e32 v2, 4, v8
	v_lshrrev_b32_e32 v1, 22, v1
	v_add_u32_e32 v1, v2, v1
	v_and_b32_e32 v1, 0xfffffc00, v1
	v_ashrrev_i32_e32 v0, 31, v8
	v_sub_u32_e32 v1, v2, v1
	v_lshrrev_b32_e32 v0, 26, v0
	v_lshrrev_b32_e32 v3, 4, v1
	v_add_u32_e32 v0, v8, v0
	v_bitop3_b32 v4, v3, v1, 32 bitop3:0x6c
	v_ashrrev_i32_e32 v1, 31, v1
	v_ashrrev_i32_e32 v0, 6, v0
	v_lshrrev_b32_e32 v1, 26, v1
	v_lshlrev_b32_e32 v3, 3, v0
	v_add_u32_e32 v1, v4, v1
	v_and_b32_e32 v3, 0x1ffff0, v3
	v_ashrrev_i32_e32 v1, 6, v1
	v_add_u32_e32 v5, v1, v3
	v_lshlrev_b32_e32 v3, 5, v0
	v_mul_i32_i24_e32 v6, 64, v1
	v_and_b32_e32 v3, 32, v3
	v_sub_u32_e32 v4, v4, v6
	v_ashrrev_i16_sdwa v4, v148, sext(v4) dst_sel:DWORD dst_unused:UNUSED_PAD src0_sel:DWORD src1_sel:BYTE_0
	v_lshl_or_b32 v5, v5, 11, v3
	v_add_u32_sdwa v136, v5, sext(v4) dst_sel:DWORD dst_unused:UNUSED_PAD src0_sel:DWORD src1_sel:WORD_0
	v_add_u32_e32 v5, 0x2000, v2
	s_lshr_b32 s68, s8, 3
	s_lshl_b32 s8, s84, 6
	v_ashrrev_i32_e32 v2, 31, v5
	s_and_b32 s75, s8, 0x100
	v_lshrrev_b32_e32 v2, 22, v2
	s_and_b32 s74, s84, 3
	s_lshl_b32 s8, s75, 12
	v_add_u32_e32 v2, v5, v2
	s_add_u32 s8, s50, s8
	v_ashrrev_i32_e32 v2, 10, v2
	s_addc_u32 s69, s51, 0
	s_lshl_b32 s76, s74, 10
	v_mul_i32_i24_e32 v6, 0x400, v2
	s_add_u32 s8, s8, s76
	v_sub_u32_e32 v5, v5, v6
	s_addc_u32 s69, s69, 0
	v_lshrrev_b32_e32 v6, 4, v5
	s_add_u32 s70, s8, 0x2d34d700
	v_bitop3_b32 v7, v6, v5, 32 bitop3:0x6c
	v_lshlrev_b32_e32 v5, 3, v2
	s_addc_u32 s71, s69, 0
	s_mov_b32 s69, s9
	v_and_b32_e32 v6, 0x1ffff0, v5
	v_ashrrev_i32_e32 v5, 31, v7
	s_lshl_b64 s[72:73], s[68:69], 20
	v_lshrrev_b32_e32 v5, 26, v5
	s_add_u32 s8, s2, s72
	v_add_u32_e32 v9, v7, v5
	s_addc_u32 s69, s7, s73
	v_ashrrev_i32_e32 v5, 6, v9
	s_add_u32 s72, s8, s76
	v_add_u32_e32 v10, v5, v6
	v_lshlrev_b32_e32 v6, 5, v2
	v_and_b32_e32 v9, 0xc0, v9
	s_addc_u32 s73, s69, 0
	v_readfirstlane_b32 s69, v8
	v_and_b32_e32 v6, 32, v6
	v_sub_u32_e32 v7, v7, v9
	s_ashr_i32 s8, s69, 6
	v_ashrrev_i16_sdwa v7, v148, sext(v7) dst_sel:DWORD dst_unused:UNUSED_PAD src0_sel:DWORD src1_sel:BYTE_0
	v_lshl_or_b32 v9, v10, 11, v6
	s_lshl_b32 s85, s8, 10
	v_readlane_b32 s76, v254, 50
	v_add_u32_sdwa v138, v9, sext(v7) dst_sel:DWORD dst_unused:UNUSED_PAD src0_sel:DWORD src1_sel:WORD_0
	s_cmp_lg_u32 s84, s99
	v_ashrrev_i32_e32 v137, 31, v136
	v_ashrrev_i32_e32 v139, 31, v138
	v_readlane_b32 s77, v254, 51
	s_cbranch_scc1 .LBB0_2101
	s_add_i32 s86, s85, 32
	v_lshlrev_b64 v[10:11], 1, v[136:137]
	s_add_i32 m0, s86, 0x10000
	v_lshl_add_u64 v[12:13], s[72:73], 0, v[10:11]
	global_load_lds_dwordx4 v[12:13], off
	v_lshlrev_b64 v[12:13], 1, v[138:139]
	v_lshl_add_u64 v[14:15], s[72:73], 0, v[12:13]
	s_add_i32 m0, s86, 0x12000
	s_nop 0
	global_load_lds_dwordx4 v[14:15], off
	v_lshl_add_u64 v[14:15], s[70:71], 0, v[10:11]
	s_mov_b32 m0, s86
	s_nop 0
	global_load_lds_dwordx4 v[14:15], off
	s_add_i32 m0, s86, 0x2000
	s_add_u32 s76, s72, 0x80000
	v_lshl_add_u64 v[14:15], s[70:71], 0, v[12:13]
	s_addc_u32 s77, s73, 0
	global_load_lds_dwordx4 v[14:15], off
	s_add_i32 m0, s86, 0x14000
	v_lshl_add_u64 v[14:15], s[76:77], 0, v[10:11]
	global_load_lds_dwordx4 v[14:15], off
	s_add_i32 m0, s86, 0x16000
	v_lshl_add_u64 v[14:15], s[76:77], 0, v[12:13]
	s_add_u32 s76, s70, 0x80000
	s_addc_u32 s77, s71, 0
	global_load_lds_dwordx4 v[14:15], off
	s_add_i32 m0, s86, 0x4000
	v_lshl_add_u64 v[10:11], s[76:77], 0, v[10:11]
	global_load_lds_dwordx4 v[10:11], off
	v_lshl_add_u64 v[10:11], s[76:77], 0, v[12:13]
	s_add_i32 m0, s86, 0x6000
	s_nop 0
	global_load_lds_dwordx4 v[10:11], off

.LBB0_2115:
	v_mov_b32_e32 v8, v250
	s_ashr_i32 s8, s8, 3
	v_bfe_i32 v1, v8, 27, 1
	v_lshlrev_b32_e32 v4, 4, v8
	v_lshrrev_b32_e32 v1, 22, v1
	v_add_u32_e32 v1, v4, v1
	v_and_b32_e32 v1, 0xfffffc00, v1
	v_ashrrev_i32_e32 v0, 31, v8
	v_sub_u32_e32 v1, v4, v1
	v_lshrrev_b32_e32 v0, 26, v0
	v_lshrrev_b32_e32 v2, 4, v1
	v_add_u32_e32 v0, v8, v0
	v_bitop3_b32 v3, v2, v1, 32 bitop3:0x6c
	v_ashrrev_i32_e32 v1, 31, v1
	v_ashrrev_i32_e32 v0, 6, v0
	v_lshrrev_b32_e32 v1, 26, v1
	v_lshlrev_b32_e32 v2, 3, v0
	v_add_u32_e32 v1, v3, v1
	s_add_i32 s8, s71, s8
	v_and_b32_e32 v2, 0x1ffff0, v2
	v_ashrrev_i32_e32 v1, 6, v1
	s_ashr_i32 s68, s8, 31
	v_add_u32_e32 v5, v1, v2
	v_lshlrev_b32_e32 v2, 5, v0
	v_mul_i32_i24_e32 v6, 64, v1
	s_lshr_b32 s68, s68, 26
	v_and_b32_e32 v2, 32, v2
	v_sub_u32_e32 v3, v3, v6
	s_add_i32 s68, s8, s68
	v_ashrrev_i16_sdwa v3, v148, sext(v3) dst_sel:DWORD dst_unused:UNUSED_PAD src0_sel:DWORD src1_sel:BYTE_0
	v_lshl_or_b32 v5, v5, 11, v2
	s_ashr_i32 s69, s68, 6
	s_and_b32 s68, s68, 0xffc0
	v_add_u32_sdwa v134, v5, sext(v3) dst_sel:DWORD dst_unused:UNUSED_PAD src0_sel:DWORD src1_sel:WORD_0
	v_add_u32_e32 v5, 0x2000, v4
	s_sub_i32 s68, s8, s68
	v_ashrrev_i32_e32 v4, 31, v5
	s_bfe_i32 s8, s68, 0x80000
	v_lshrrev_b32_e32 v4, 22, v4
	s_bfe_u32 s8, s8, 0x3000c
	v_add_u32_e32 v4, v5, v4
	s_add_i32 s70, s68, s8
	v_ashrrev_i32_e32 v4, 10, v4
	s_bfe_i32 s8, s70, 0x80000
	s_and_b32 s70, s70, 0xf8
	v_mul_i32_i24_e32 v6, 0x400, v4
	s_sub_i32 s68, s68, s70
	v_sub_u32_e32 v5, v5, v6
	s_lshl_b32 s69, s69, 3
	s_sext_i32_i8 s68, s68
	v_lshrrev_b32_e32 v6, 4, v5
	s_add_i32 s68, s69, s68
	v_bitop3_b32 v7, v6, v5, 32 bitop3:0x6c
	v_lshlrev_b32_e32 v5, 3, v4
	s_sext_i32_i16 s8, s8
	s_ashr_i32 s69, s68, 31
	v_and_b32_e32 v6, 0x1ffff0, v5
	v_ashrrev_i32_e32 v5, 31, v7
	s_lshr_b32 s8, s8, 3
	s_lshl_b64 s[72:73], s[68:69], 20
	v_lshrrev_b32_e32 v5, 26, v5
	s_add_u32 s70, s0, s72
	v_add_u32_e32 v9, v7, v5
	s_addc_u32 s71, s1, s73
	s_bfe_i64 s[74:75], s[8:9], 0x100000
	v_ashrrev_i32_e32 v5, 6, v9
	s_lshl_b64 s[74:75], s[74:75], 20
	v_add_u32_e32 v10, v5, v6
	v_lshlrev_b32_e32 v6, 5, v4
	v_and_b32_e32 v9, 0xc0, v9
	s_add_u32 s76, s2, s74
	v_readfirstlane_b32 s69, v8
	v_and_b32_e32 v6, 32, v6
	v_sub_u32_e32 v7, v7, v9
	s_addc_u32 s77, s7, s75
	s_ashr_i32 s85, s69, 6
	v_ashrrev_i16_sdwa v7, v148, sext(v7) dst_sel:DWORD dst_unused:UNUSED_PAD src0_sel:DWORD src1_sel:BYTE_0
	v_lshl_or_b32 v9, v10, 11, v6
	s_lshl_b32 s86, s85, 10
	v_readlane_b32 s88, v254, 50
	v_add_u32_sdwa v136, v9, sext(v7) dst_sel:DWORD dst_unused:UNUSED_PAD src0_sel:DWORD src1_sel:WORD_0
	s_cmp_lg_u32 s84, s99
	v_ashrrev_i32_e32 v135, 31, v134
	v_ashrrev_i32_e32 v137, 31, v136
	v_readlane_b32 s89, v254, 51
	s_cbranch_scc1 .LBB0_2117
	s_add_i32 s84, s86, 32
	v_lshlrev_b64 v[10:11], 1, v[134:135]
	s_add_i32 m0, s84, 0x10000
	v_lshl_add_u64 v[12:13], s[76:77], 0, v[10:11]
	global_load_lds_dwordx4 v[12:13], off
	v_lshlrev_b64 v[12:13], 1, v[136:137]
	v_lshl_add_u64 v[14:15], s[76:77], 0, v[12:13]
	s_add_i32 m0, s84, 0x12000
	s_nop 0
	global_load_lds_dwordx4 v[14:15], off
	v_lshl_add_u64 v[14:15], s[70:71], 0, v[10:11]
	s_mov_b32 m0, s84
	s_nop 0
	global_load_lds_dwordx4 v[14:15], off
	s_add_i32 m0, s84, 0x2000
	s_add_u32 s88, s76, 0x80000
	v_lshl_add_u64 v[14:15], s[70:71], 0, v[12:13]
	s_addc_u32 s89, s77, 0
	global_load_lds_dwordx4 v[14:15], off
	s_add_i32 m0, s84, 0x14000
	v_lshl_add_u64 v[14:15], s[88:89], 0, v[10:11]
	global_load_lds_dwordx4 v[14:15], off
	s_add_i32 m0, s84, 0x16000
	v_lshl_add_u64 v[14:15], s[88:89], 0, v[12:13]
	s_add_u32 s88, s70, 0x80000
	s_addc_u32 s89, s71, 0
	global_load_lds_dwordx4 v[14:15], off
	s_add_i32 m0, s84, 0x4000
	v_lshl_add_u64 v[10:11], s[88:89], 0, v[10:11]
	global_load_lds_dwordx4 v[10:11], off
	v_lshl_add_u64 v[10:11], s[88:89], 0, v[12:13]
	s_add_i32 m0, s84, 0x6000
	s_nop 0
	global_load_lds_dwordx4 v[10:11], off

	.amdhsa_kernel _Z4mega6Params
		.amdhsa_group_segment_fixed_size 32
		.amdhsa_private_segment_fixed_size 0
		.amdhsa_kernarg_size 512
		.amdhsa_user_sgpr_count 2
		.amdhsa_user_sgpr_dispatch_ptr 0
		.amdhsa_user_sgpr_queue_ptr 0
		.amdhsa_user_sgpr_kernarg_segment_ptr 1
		.amdhsa_user_sgpr_dispatch_id 0
		.amdhsa_user_sgpr_kernarg_preload_length 0
		.amdhsa_user_sgpr_kernarg_preload_offset 0
		.amdhsa_user_sgpr_private_segment_size 0
		.amdhsa_uses_dynamic_stack 0
		.amdhsa_enable_private_segment 0
		.amdhsa_system_sgpr_workgroup_id_x 1
		.amdhsa_system_sgpr_workgroup_id_y 0
		.amdhsa_system_sgpr_workgroup_id_z 0
		.amdhsa_system_sgpr_workgroup_info 0
		.amdhsa_system_vgpr_workitem_id 2
		.amdhsa_next_free_vgpr 256
		.amdhsa_next_free_sgpr 102
		.amdhsa_accum_offset 256
		.amdhsa_reserve_vcc 1
		.amdhsa_float_round_mode_32 0
		.amdhsa_float_round_mode_16_64 0
		.amdhsa_float_denorm_mode_32 3
		.amdhsa_float_denorm_mode_16_64 3
		.amdhsa_dx10_clamp 1
		.amdhsa_ieee_mode 1
		.amdhsa_fp16_overflow 0
		.amdhsa_tg_split 0
		.amdhsa_exception_fp_ieee_invalid_op 0
		.amdhsa_exception_fp_denorm_src 0
		.amdhsa_exception_fp_ieee_div_zero 0
		.amdhsa_exception_fp_ieee_overflow 0
		.amdhsa_exception_fp_ieee_underflow 0
		.amdhsa_exception_fp_ieee_inexact 0
		.amdhsa_exception_int_div_zero 0
	.end_amdhsa_kernel

amdhsa.kernels:
  - .agpr_count:     0
    .args:
      - .offset:         0
        .size:           256
        .value_kind:     by_value
      - .offset:         256
        .size:           4
        .value_kind:     hidden_block_count_x
      - .offset:         260
        .size:           4
        .value_kind:     hidden_block_count_y
      - .offset:         264
        .size:           4
        .value_kind:     hidden_block_count_z
      - .offset:         268
        .size:           2
        .value_kind:     hidden_group_size_x
      - .offset:         270
        .size:           2
        .value_kind:     hidden_group_size_y
      - .offset:         272
        .size:           2
        .value_kind:     hidden_group_size_z
      - .offset:         274
        .size:           2
        .value_kind:     hidden_remainder_x
      - .offset:         276
        .size:           2
        .value_kind:     hidden_remainder_y
      - .offset:         278
        .size:           2
        .value_kind:     hidden_remainder_z
      - .offset:         296
        .size:           8
        .value_kind:     hidden_global_offset_x
      - .offset:         304
        .size:           8
        .value_kind:     hidden_global_offset_y
      - .offset:         312
        .size:           8
        .value_kind:     hidden_global_offset_z
      - .offset:         320
        .size:           2
        .value_kind:     hidden_grid_dims
      - .offset:         344
        .size:           8
        .value_kind:     hidden_multigrid_sync_arg
      - .offset:         376
        .size:           4
        .value_kind:     hidden_dynamic_lds_size
    .group_segment_fixed_size: 32
    .kernarg_segment_align: 8
    .kernarg_segment_size: 512
    .language:       OpenCL C
    .language_version:
      - 2
      - 0
    .max_flat_workgroup_size: 512
    .name:           _Z4mega6Params
    .private_segment_fixed_size: 0
    .sgpr_count:     108
    .sgpr_spill_count: 76
    .symbol:         _Z4mega6Params.kd
    .uniform_work_group_size: 1
    .uses_dynamic_stack: false
    .vgpr_count:     256
    .vgpr_spill_count: 0
    .wavefront_size: 64
